# barriers 2-19: hand-written thread-0 body (per-XCD arrive, leader wbl2 + TOP add, all poll TOP, no divisions)
# speedup vs baseline: 1.0582x; 1.0028x over previous
_Z8fwd_mega6Params:
	s_mov_b32 s98, 1
	s_load_dwordx4 s[4:7], s[0:1], 0x100
	v_and_b32_e32 v137, 0x3ff, v0
	v_writelane_b32 v242, s2, 0
	s_waitcnt lgkmcnt(0)
	v_writelane_b32 v242, s4, 1
	s_nop 1
	v_writelane_b32 v242, s5, 2
	v_writelane_b32 v242, s6, 3
	v_writelane_b32 v242, s7, 4
	v_cmp_eq_u32_e64 s[4:5], 0, v137
	s_mov_b64 s[2:3], exec
	s_nop 0
	v_writelane_b32 v242, s4, 5
	s_nop 1
	v_writelane_b32 v242, s5, 6
	s_and_b64 s[4:5], s[2:3], s[4:5]
	s_mov_b64 exec, s[4:5]
	s_add_i32 s4, 0, 0x12008
	v_mov_b32_e32 v2, 0
	v_mov_b32_e32 v3, v2
	v_mov_b32_e32 v1, s4
	ds_write_b64 v1, v[2:3]
	s_or_b64 exec, exec, s[2:3]
	s_load_dwordx4 s[4:7], s[0:1], 0x100
	s_waitcnt lgkmcnt(0)
	s_barrier
	s_add_u32 s2, s6, 0x30f4100
	s_addc_u32 s3, s7, 0
	v_writelane_b32 v242, s2, 7
	s_nop 1
	v_writelane_b32 v242, s3, 8
	s_getreg_b32 s2, hwreg(HW_REG_XCC_ID, 0, 4)
	s_and_b32 s2, s2, 15
	v_writelane_b32 v242, s2, 9
	s_mov_b64 s[2:3], exec
	v_readlane_b32 s4, v242, 5
	v_readlane_b32 s5, v242, 6
	s_and_b64 s[4:5], s[2:3], s[4:5]
	s_mov_b64 exec, s[4:5]
	s_cbranch_execz .LBB0_5
	s_mov_b64 s[4:5], exec
	v_mbcnt_lo_u32_b32 v1, s4, 0
	v_mbcnt_hi_u32_b32 v1, s5, v1
	v_cmp_eq_u32_e32 vcc, 0, v1
	s_and_b64 s[6:7], exec, vcc
	s_mov_b64 exec, s[6:7]
	s_cbranch_execz .LBB0_5
	v_readlane_b32 s6, v242, 9
	s_bcnt1_i32_b64 s4, s[4:5]
	s_lshl_b32 s6, s6, 8
	v_mov_b32_e32 v2, s4
	v_readlane_b32 s4, v242, 7
	v_mov_b32_e32 v1, s6
	v_readlane_b32 s5, v242, 8
	s_nop 4
	global_atomic_add v1, v2, s[4:5] offset:1024

.LBB0_210:
	s_or_b64 exec, exec, s[4:5]
	s_mov_b64 s[4:5], exec
	v_mbcnt_lo_u32_b32 v0, s4, 0
	v_mbcnt_hi_u32_b32 v0, s5, v0
	v_cmp_eq_u32_e32 vcc, 0, v0
	s_waitcnt vmcnt(0)
	buffer_inv sc1
	s_and_saveexec_b64 s[6:7], vcc
	s_cbranch_execz .LBB0_212
	s_bcnt1_i32_b64 s4, s[4:5]
	v_mov_b32_e32 v0, 0x2000
	v_mov_b32_e32 v1, s4
	s_nop 0

.LBB0_218:
	s_or_b64 exec, exec, s[0:1]
	s_waitcnt vmcnt(0)
	s_barrier
	s_mov_b64 s[0:1], exec
	v_readlane_b32 s2, v242, 5
	v_readlane_b32 s3, v242, 6
	s_and_b64 s[2:3], s[0:1], s[2:3]
	s_xor_b64 s[0:1], s[2:3], s[0:1]
	s_mov_b64 exec, s[2:3]
	s_cbranch_execz .LBB0_271
	s_waitcnt vmcnt(0) lgkmcnt(0)
	v_mov_b32_e32 v0, 0x12008
	ds_read_b64 v[0:1], v0
	v_readlane_b32 s2, v242, 7
	v_readlane_b32 s3, v242, 8
	v_readlane_b32 s4, v242, 9
	v_mov_b32_e32 v2, 0
	v_mov_b32_e32 v3, 1
	s_lshl_b32 s4, s4, 8
	s_add_i32 s4, s4, 0x1400
	s_add_u32 s6, s2, s4
	s_addc_u32 s7, s3, 0
	s_add_u32 s8, s2, 0x3400
	s_addc_u32 s9, s3, 0
	s_add_i32 s10, s98, 1
	global_atomic_add v4, v2, v3, s[6:7] sc0
	s_waitcnt lgkmcnt(0)
	v_readfirstlane_b32 s11, v0
	v_readfirstlane_b32 s12, v1
	s_mul_i32 s13, s10, s11
	s_mul_i32 s12, s10, s12
	s_waitcnt vmcnt(0)
	v_readfirstlane_b32 s14, v4
	s_add_i32 s14, s14, 1
	s_cmp_lg_u32 s14, s13
	s_cbranch_scc1 .Lxb1_wait
	buffer_wbl2 sc1
	s_waitcnt vmcnt(0)
	global_atomic_add v2, v3, s[8:9]
.Lxb1_wait:
	s_mov_b32 s15, 0
.Lxb1_spin:
	global_load_dword v4, v2, s[8:9] sc1
	s_waitcnt vmcnt(0)
	v_readfirstlane_b32 s14, v4
	s_cmp_ge_u32 s14, s12
	s_cbranch_scc1 .Lxb1_done
	s_sleep 1
	s_add_i32 s15, s15, 1
	s_cmp_lt_u32 s15, 0x4000
	s_cbranch_scc1 .Lxb1_spin
.Lxb1_done:
	buffer_inv sc1
	s_waitcnt vmcnt(0)
	s_mov_b32 s98, s10

.LBB0_782:
	s_waitcnt vmcnt(0)
	s_waitcnt vmcnt(63) expcnt(7) lgkmcnt(15)
	s_barrier
	s_mov_b64 s[0:1], exec
	v_readlane_b32 s2, v242, 5
	v_readlane_b32 s3, v242, 6
	v_readlane_b32 s94, v241, 27
	s_and_b64 s[2:3], s[0:1], s[2:3]
	v_readlane_b32 s66, v241, 13
	v_readlane_b32 s95, v241, 28
	s_mov_b64 exec, s[2:3]
	s_cbranch_execz .LBB0_834
	s_waitcnt vmcnt(0) lgkmcnt(0)
	v_mov_b32_e32 v0, 0x12008
	ds_read_b64 v[0:1], v0
	v_readlane_b32 s2, v242, 7
	v_readlane_b32 s3, v242, 8
	v_readlane_b32 s4, v242, 9
	v_mov_b32_e32 v2, 0
	v_mov_b32_e32 v3, 1
	s_lshl_b32 s4, s4, 8
	s_add_i32 s4, s4, 0x1400
	s_add_u32 s6, s2, s4
	s_addc_u32 s7, s3, 0
	s_add_u32 s8, s2, 0x3400
	s_addc_u32 s9, s3, 0
	s_add_i32 s10, s98, 1
	global_atomic_add v4, v2, v3, s[6:7] sc0
	s_waitcnt lgkmcnt(0)
	v_readfirstlane_b32 s11, v0
	v_readfirstlane_b32 s12, v1
	s_mul_i32 s13, s10, s11
	s_mul_i32 s12, s10, s12
	s_waitcnt vmcnt(0)
	v_readfirstlane_b32 s14, v4
	s_add_i32 s14, s14, 1
	s_cmp_lg_u32 s14, s13
	s_cbranch_scc1 .Lxb2_wait
	buffer_wbl2 sc1
	s_waitcnt vmcnt(0)
	global_atomic_add v2, v3, s[8:9]

.LBB0_853:
	s_waitcnt vmcnt(0)
	s_barrier
	s_mov_b64 s[0:1], exec
	v_readlane_b32 s2, v242, 5
	v_readlane_b32 s3, v242, 6
	s_and_b64 s[2:3], s[0:1], s[2:3]
	s_mov_b64 exec, s[2:3]
	s_cbranch_execz .LBB0_905
	s_waitcnt vmcnt(0) lgkmcnt(0)
	v_mov_b32_e32 v0, 0x12008
	ds_read_b64 v[0:1], v0
	v_readlane_b32 s2, v242, 7
	v_readlane_b32 s3, v242, 8
	v_readlane_b32 s4, v242, 9
	v_mov_b32_e32 v2, 0
	v_mov_b32_e32 v3, 1
	s_lshl_b32 s4, s4, 8
	s_add_i32 s4, s4, 0x1400
	s_add_u32 s6, s2, s4
	s_addc_u32 s7, s3, 0
	s_add_u32 s8, s2, 0x3400
	s_addc_u32 s9, s3, 0
	s_add_i32 s10, s98, 1
	global_atomic_add v4, v2, v3, s[6:7] sc0
	s_waitcnt lgkmcnt(0)
	v_readfirstlane_b32 s11, v0
	v_readfirstlane_b32 s12, v1
	s_mul_i32 s13, s10, s11
	s_mul_i32 s12, s10, s12
	s_waitcnt vmcnt(0)
	v_readfirstlane_b32 s14, v4
	s_add_i32 s14, s14, 1
	s_cmp_lg_u32 s14, s13
	s_cbranch_scc1 .Lxb3_wait
	buffer_wbl2 sc1
	s_waitcnt vmcnt(0)
	global_atomic_add v2, v3, s[8:9]

.LBB0_978:
	s_waitcnt vmcnt(0)
	s_barrier
	s_mov_b64 s[0:1], exec
	v_readlane_b32 s2, v242, 5
	v_readlane_b32 s3, v242, 6
	v_readlane_b32 s44, v242, 58
	v_readlane_b32 s72, v242, 54
	v_readlane_b32 s58, v242, 56
	s_and_b64 s[2:3], s[0:1], s[2:3]
	v_readlane_b32 s45, v242, 59
	v_readlane_b32 s73, v242, 55
	v_readlane_b32 s59, v242, 57
	s_mov_b64 exec, s[2:3]
	s_cbranch_execz .LBB0_1030
	s_waitcnt vmcnt(0) lgkmcnt(0)
	v_mov_b32_e32 v0, 0x12008
	ds_read_b64 v[0:1], v0
	v_readlane_b32 s2, v242, 7
	v_readlane_b32 s3, v242, 8
	v_readlane_b32 s4, v242, 9
	v_mov_b32_e32 v2, 0
	v_mov_b32_e32 v3, 1
	s_lshl_b32 s4, s4, 8
	s_add_i32 s4, s4, 0x1400
	s_add_u32 s6, s2, s4
	s_addc_u32 s7, s3, 0
	s_add_u32 s8, s2, 0x3400
	s_addc_u32 s9, s3, 0
	s_add_i32 s10, s98, 1
	global_atomic_add v4, v2, v3, s[6:7] sc0
	s_waitcnt lgkmcnt(0)
	v_readfirstlane_b32 s11, v0
	v_readfirstlane_b32 s12, v1
	s_mul_i32 s13, s10, s11
	s_mul_i32 s12, s10, s12
	s_waitcnt vmcnt(0)
	v_readfirstlane_b32 s14, v4
	s_add_i32 s14, s14, 1
	s_cmp_lg_u32 s14, s13
	s_cbranch_scc1 .Lxb4_wait
	buffer_wbl2 sc1
	s_waitcnt vmcnt(0)
	global_atomic_add v2, v3, s[8:9]

.LBB0_1033:
	s_or_b64 exec, exec, s[0:1]
	s_waitcnt vmcnt(0)
	s_barrier
	s_mov_b64 s[0:1], exec
	v_readlane_b32 s2, v242, 5
	v_readlane_b32 s3, v242, 6
	s_and_b64 s[2:3], s[0:1], s[2:3]
	v_readlane_b32 s41, v241, 14
	s_mov_b64 exec, s[2:3]
	s_cbranch_execz .LBB0_1085
	s_waitcnt vmcnt(0) lgkmcnt(0)
	v_mov_b32_e32 v0, 0x12008
	ds_read_b64 v[0:1], v0
	v_readlane_b32 s2, v242, 7
	v_readlane_b32 s3, v242, 8
	v_readlane_b32 s4, v242, 9
	v_mov_b32_e32 v2, 0
	v_mov_b32_e32 v3, 1
	s_lshl_b32 s4, s4, 8
	s_add_i32 s4, s4, 0x1400
	s_add_u32 s6, s2, s4
	s_addc_u32 s7, s3, 0
	s_add_u32 s8, s2, 0x3400
	s_addc_u32 s9, s3, 0
	s_add_i32 s10, s98, 1
	global_atomic_add v4, v2, v3, s[6:7] sc0
	s_waitcnt lgkmcnt(0)
	v_readfirstlane_b32 s11, v0
	v_readfirstlane_b32 s12, v1
	s_mul_i32 s13, s10, s11
	s_mul_i32 s12, s10, s12
	s_waitcnt vmcnt(0)
	v_readfirstlane_b32 s14, v4
	s_add_i32 s14, s14, 1
	s_cmp_lg_u32 s14, s13
	s_cbranch_scc1 .Lxb5_wait
	buffer_wbl2 sc1
	s_waitcnt vmcnt(0)
	global_atomic_add v2, v3, s[8:9]

.LBB0_1091:
	s_waitcnt vmcnt(0)
	s_waitcnt vmcnt(63) expcnt(7) lgkmcnt(15)
	s_barrier
	s_mov_b64 s[0:1], exec
	v_readlane_b32 s2, v242, 5
	v_readlane_b32 s3, v242, 6
	s_and_b64 s[2:3], s[0:1], s[2:3]
	s_mov_b64 exec, s[2:3]
	s_cbranch_execz .LBB0_1143
	s_waitcnt vmcnt(0) lgkmcnt(0)
	v_mov_b32_e32 v0, 0x12008
	ds_read_b64 v[0:1], v0
	v_readlane_b32 s2, v242, 7
	v_readlane_b32 s3, v242, 8
	v_readlane_b32 s4, v242, 9
	v_mov_b32_e32 v2, 0
	v_mov_b32_e32 v3, 1
	s_lshl_b32 s4, s4, 8
	s_add_i32 s4, s4, 0x1400
	s_add_u32 s6, s2, s4
	s_addc_u32 s7, s3, 0
	s_add_u32 s8, s2, 0x3400
	s_addc_u32 s9, s3, 0
	s_add_i32 s10, s98, 1
	global_atomic_add v4, v2, v3, s[6:7] sc0
	s_waitcnt lgkmcnt(0)
	v_readfirstlane_b32 s11, v0
	v_readfirstlane_b32 s12, v1
	s_mul_i32 s13, s10, s11
	s_mul_i32 s12, s10, s12
	s_waitcnt vmcnt(0)
	v_readfirstlane_b32 s14, v4
	s_add_i32 s14, s14, 1
	s_cmp_lg_u32 s14, s13
	s_cbranch_scc1 .Lxb6_wait
	buffer_wbl2 sc1
	s_waitcnt vmcnt(0)
	global_atomic_add v2, v3, s[8:9]

.LBB0_1149:
	s_or_b64 exec, exec, s[2:3]
	s_waitcnt vmcnt(0)
	s_barrier
	s_mov_b64 s[0:1], exec
	v_readlane_b32 s2, v242, 5
	v_readlane_b32 s3, v242, 6
	s_and_b64 s[2:3], s[0:1], s[2:3]
	s_mov_b64 exec, s[2:3]
	s_cbranch_execz .LBB0_1201
	s_waitcnt vmcnt(0) lgkmcnt(0)
	v_mov_b32_e32 v0, 0x12008
	ds_read_b64 v[0:1], v0
	v_readlane_b32 s2, v242, 7
	v_readlane_b32 s3, v242, 8
	v_readlane_b32 s4, v242, 9
	v_mov_b32_e32 v2, 0
	v_mov_b32_e32 v3, 1
	s_lshl_b32 s4, s4, 8
	s_add_i32 s4, s4, 0x1400
	s_add_u32 s6, s2, s4
	s_addc_u32 s7, s3, 0
	s_add_u32 s8, s2, 0x3400
	s_addc_u32 s9, s3, 0
	s_add_i32 s10, s98, 1
	global_atomic_add v4, v2, v3, s[6:7] sc0
	s_waitcnt lgkmcnt(0)
	v_readfirstlane_b32 s11, v0
	v_readfirstlane_b32 s12, v1
	s_mul_i32 s13, s10, s11
	s_mul_i32 s12, s10, s12
	s_waitcnt vmcnt(0)
	v_readfirstlane_b32 s14, v4
	s_add_i32 s14, s14, 1
	s_cmp_lg_u32 s14, s13
	s_cbranch_scc1 .Lxb7_wait
	buffer_wbl2 sc1
	s_waitcnt vmcnt(0)
	global_atomic_add v2, v3, s[8:9]

.LBB0_1207:
	s_waitcnt vmcnt(0)
	s_barrier
	s_mov_b64 s[0:1], exec
	v_readlane_b32 s2, v242, 5
	v_readlane_b32 s3, v242, 6
	v_readlane_b32 s46, v242, 52
	s_and_b64 s[2:3], s[0:1], s[2:3]
	v_readlane_b32 s47, v242, 53
	s_mov_b64 exec, s[2:3]
	s_cbranch_execz .LBB0_1259
	s_waitcnt vmcnt(0) lgkmcnt(0)
	v_mov_b32_e32 v0, 0x12008
	ds_read_b64 v[0:1], v0
	v_readlane_b32 s2, v242, 7
	v_readlane_b32 s3, v242, 8
	v_readlane_b32 s4, v242, 9
	v_mov_b32_e32 v2, 0
	v_mov_b32_e32 v3, 1
	s_lshl_b32 s4, s4, 8
	s_add_i32 s4, s4, 0x1400
	s_add_u32 s6, s2, s4
	s_addc_u32 s7, s3, 0
	s_add_u32 s8, s2, 0x3400
	s_addc_u32 s9, s3, 0
	s_add_i32 s10, s98, 1
	global_atomic_add v4, v2, v3, s[6:7] sc0
	s_waitcnt lgkmcnt(0)
	v_readfirstlane_b32 s11, v0
	v_readfirstlane_b32 s12, v1
	s_mul_i32 s13, s10, s11
	s_mul_i32 s12, s10, s12
	s_waitcnt vmcnt(0)
	v_readfirstlane_b32 s14, v4
	s_add_i32 s14, s14, 1
	s_cmp_lg_u32 s14, s13
	s_cbranch_scc1 .Lxb8_wait
	buffer_wbl2 sc1
	s_waitcnt vmcnt(0)
	global_atomic_add v2, v3, s[8:9]

.Lrp20_done:
.LBB0_1322:
	s_or_b64 exec, exec, s[0:1]
	s_waitcnt vmcnt(0)
	s_barrier
	s_mov_b64 s[0:1], exec
	v_readlane_b32 s2, v242, 5
	v_readlane_b32 s3, v242, 6
	s_and_b64 s[2:3], s[0:1], s[2:3]
	s_mov_b64 exec, s[2:3]
	s_cbranch_execz .LBB0_1374
	s_waitcnt vmcnt(0) lgkmcnt(0)
	v_mov_b32_e32 v0, 0x12008
	ds_read_b64 v[0:1], v0
	v_readlane_b32 s2, v242, 7
	v_readlane_b32 s3, v242, 8
	v_readlane_b32 s4, v242, 9
	v_mov_b32_e32 v2, 0
	v_mov_b32_e32 v3, 1
	s_lshl_b32 s4, s4, 8
	s_add_i32 s4, s4, 0x1400
	s_add_u32 s6, s2, s4
	s_addc_u32 s7, s3, 0
	s_add_u32 s8, s2, 0x3400
	s_addc_u32 s9, s3, 0
	s_add_i32 s10, s98, 1
	global_atomic_add v4, v2, v3, s[6:7] sc0
	s_waitcnt lgkmcnt(0)
	v_readfirstlane_b32 s11, v0
	v_readfirstlane_b32 s12, v1
	s_mul_i32 s13, s10, s11
	s_mul_i32 s12, s10, s12
	s_waitcnt vmcnt(0)
	v_readfirstlane_b32 s14, v4
	s_add_i32 s14, s14, 1
	s_cmp_lg_u32 s14, s13
	s_cbranch_scc1 .Lxb10_wait
	buffer_wbl2 sc1
	s_waitcnt vmcnt(0)
	global_atomic_add v2, v3, s[8:9]

.LBB0_1779:
	s_waitcnt vmcnt(0)
	s_waitcnt vmcnt(63) expcnt(7) lgkmcnt(15)
	s_barrier
	s_mov_b64 s[0:1], exec
	v_readlane_b32 s2, v242, 5
	v_readlane_b32 s3, v242, 6
	v_readlane_b32 s76, v241, 16
	v_readlane_b32 s80, v241, 18
	s_and_b64 s[2:3], s[0:1], s[2:3]
	v_readlane_b32 s77, v241, 17
	v_readlane_b32 s78, v241, 15
	v_readlane_b32 s79, v241, 20
	v_readlane_b32 s81, v241, 19
	s_mov_b64 exec, s[2:3]
	s_cbranch_execz .LBB0_1831
	s_waitcnt vmcnt(0) lgkmcnt(0)
	v_mov_b32_e32 v0, 0x12008
	ds_read_b64 v[0:1], v0
	v_readlane_b32 s2, v242, 7
	v_readlane_b32 s3, v242, 8
	v_readlane_b32 s4, v242, 9
	v_mov_b32_e32 v2, 0
	v_mov_b32_e32 v3, 1
	s_lshl_b32 s4, s4, 8
	s_add_i32 s4, s4, 0x1400
	s_add_u32 s6, s2, s4
	s_addc_u32 s7, s3, 0
	s_add_u32 s8, s2, 0x3400
	s_addc_u32 s9, s3, 0
	s_add_i32 s10, s98, 1
	global_atomic_add v4, v2, v3, s[6:7] sc0
	s_waitcnt lgkmcnt(0)
	v_readfirstlane_b32 s11, v0
	v_readfirstlane_b32 s12, v1
	s_mul_i32 s13, s10, s11
	s_mul_i32 s12, s10, s12
	s_waitcnt vmcnt(0)
	v_readfirstlane_b32 s14, v4
	s_add_i32 s14, s14, 1
	s_cmp_lg_u32 s14, s13
	s_cbranch_scc1 .Lxb11_wait
	buffer_wbl2 sc1
	s_waitcnt vmcnt(0)
	global_atomic_add v2, v3, s[8:9]

.LBB0_2031:
	s_or_b64 exec, exec, s[0:1]
	s_waitcnt vmcnt(0)
	s_barrier
	s_mov_b64 s[0:1], exec
	v_readlane_b32 s2, v242, 5
	v_readlane_b32 s3, v242, 6
	v_readlane_b32 s44, v241, 45
	s_and_b64 s[2:3], s[0:1], s[2:3]
	v_readlane_b32 s45, v241, 46
	v_readlane_b32 s56, v242, 56
	v_readlane_b32 s57, v242, 54
	s_mov_b64 exec, s[2:3]
	s_cbranch_execz .LBB0_2083
	s_waitcnt vmcnt(0) lgkmcnt(0)
	v_mov_b32_e32 v0, 0x12008
	ds_read_b64 v[0:1], v0
	v_readlane_b32 s2, v242, 7
	v_readlane_b32 s3, v242, 8
	v_readlane_b32 s4, v242, 9
	v_mov_b32_e32 v2, 0
	v_mov_b32_e32 v3, 1
	s_lshl_b32 s4, s4, 8
	s_add_i32 s4, s4, 0x1400
	s_add_u32 s6, s2, s4
	s_addc_u32 s7, s3, 0
	s_add_u32 s8, s2, 0x3400
	s_addc_u32 s9, s3, 0
	s_add_i32 s10, s98, 1
	global_atomic_add v4, v2, v3, s[6:7] sc0
	s_waitcnt lgkmcnt(0)
	v_readfirstlane_b32 s11, v0
	v_readfirstlane_b32 s12, v1
	s_mul_i32 s13, s10, s11
	s_mul_i32 s12, s10, s12
	s_waitcnt vmcnt(0)
	v_readfirstlane_b32 s14, v4
	s_add_i32 s14, s14, 1
	s_cmp_lg_u32 s14, s13
	s_cbranch_scc1 .Lxb14_wait
	buffer_wbl2 sc1
	s_waitcnt vmcnt(0)
	global_atomic_add v2, v3, s[8:9]

.LBB0_2147:
	s_or_b64 exec, exec, s[0:1]
	s_waitcnt vmcnt(0)
	s_barrier
	s_mov_b64 s[0:1], exec
	v_readlane_b32 s2, v242, 5
	v_readlane_b32 s3, v242, 6
	s_and_b64 s[2:3], s[0:1], s[2:3]
	s_mov_b64 exec, s[2:3]
	s_cbranch_execz .LBB0_2199
	s_waitcnt vmcnt(0) lgkmcnt(0)
	v_mov_b32_e32 v0, 0x12008
	ds_read_b64 v[0:1], v0
	v_readlane_b32 s2, v242, 7
	v_readlane_b32 s3, v242, 8
	v_readlane_b32 s4, v242, 9
	v_mov_b32_e32 v2, 0
	v_mov_b32_e32 v3, 1
	s_lshl_b32 s4, s4, 8
	s_add_i32 s4, s4, 0x1400
	s_add_u32 s6, s2, s4
	s_addc_u32 s7, s3, 0
	s_add_u32 s8, s2, 0x3400
	s_addc_u32 s9, s3, 0
	s_add_i32 s10, s98, 1
	global_atomic_add v4, v2, v3, s[6:7] sc0
	s_waitcnt lgkmcnt(0)
	v_readfirstlane_b32 s11, v0
	v_readfirstlane_b32 s12, v1
	s_mul_i32 s13, s10, s11
	s_mul_i32 s12, s10, s12
	s_waitcnt vmcnt(0)
	v_readfirstlane_b32 s14, v4
	s_add_i32 s14, s14, 1
	s_cmp_lg_u32 s14, s13
	s_cbranch_scc1 .Lxb16_wait
	buffer_wbl2 sc1
	s_waitcnt vmcnt(0)
	global_atomic_add v2, v3, s[8:9]

.LBB0_2205:
	s_waitcnt vmcnt(0)
	s_barrier
	s_mov_b64 s[0:1], exec
	v_readlane_b32 s2, v242, 5
	v_readlane_b32 s3, v242, 6
	v_readlane_b32 s36, v241, 29
	s_and_b64 s[2:3], s[0:1], s[2:3]
	v_readlane_b32 s48, v241, 41
	v_readlane_b32 s49, v241, 42
	v_readlane_b32 s37, v241, 30
	v_readlane_b32 s38, v241, 31
	v_readlane_b32 s39, v241, 32
	v_readlane_b32 s40, v241, 33
	v_readlane_b32 s41, v241, 34
	v_readlane_b32 s42, v241, 35
	v_readlane_b32 s43, v241, 36
	v_readlane_b32 s44, v241, 37
	v_readlane_b32 s45, v241, 38
	v_readlane_b32 s46, v241, 39
	v_readlane_b32 s47, v241, 40
	v_readlane_b32 s50, v241, 43
	v_readlane_b32 s51, v241, 44
	s_mov_b64 exec, s[2:3]
	s_cbranch_execz .LBB0_2257
	s_waitcnt vmcnt(0) lgkmcnt(0)
	v_mov_b32_e32 v0, 0x12008
	ds_read_b64 v[0:1], v0
	v_readlane_b32 s2, v242, 7
	v_readlane_b32 s3, v242, 8
	v_readlane_b32 s4, v242, 9
	v_mov_b32_e32 v2, 0
	v_mov_b32_e32 v3, 1
	s_lshl_b32 s4, s4, 8
	s_add_i32 s4, s4, 0x1400
	s_add_u32 s6, s2, s4
	s_addc_u32 s7, s3, 0
	s_add_u32 s8, s2, 0x3400
	s_addc_u32 s9, s3, 0
	s_add_i32 s10, s98, 1
	global_atomic_add v4, v2, v3, s[6:7] sc0
	s_waitcnt lgkmcnt(0)
	v_readfirstlane_b32 s11, v0
	v_readfirstlane_b32 s12, v1
	s_mul_i32 s13, s10, s11
	s_mul_i32 s12, s10, s12
	s_waitcnt vmcnt(0)
	v_readfirstlane_b32 s14, v4
	s_add_i32 s14, s14, 1
	s_cmp_lg_u32 s14, s13
	s_cbranch_scc1 .Lxb17_wait
	buffer_wbl2 sc1
	s_waitcnt vmcnt(0)
	global_atomic_add v2, v3, s[8:9]

	.amdhsa_kernel _Z8fwd_mega6Params
		.amdhsa_group_segment_fixed_size 0
		.amdhsa_private_segment_fixed_size 0
		.amdhsa_kernarg_size 536
		.amdhsa_user_sgpr_count 2
		.amdhsa_user_sgpr_dispatch_ptr 0
		.amdhsa_user_sgpr_queue_ptr 0
		.amdhsa_user_sgpr_kernarg_segment_ptr 1
		.amdhsa_user_sgpr_dispatch_id 0
		.amdhsa_user_sgpr_kernarg_preload_length 0
		.amdhsa_user_sgpr_kernarg_preload_offset 0
		.amdhsa_user_sgpr_private_segment_size 0
		.amdhsa_uses_dynamic_stack 0
		.amdhsa_enable_private_segment 0
		.amdhsa_system_sgpr_workgroup_id_x 1
		.amdhsa_system_sgpr_workgroup_id_y 0
		.amdhsa_system_sgpr_workgroup_id_z 0
		.amdhsa_system_sgpr_workgroup_info 0
		.amdhsa_system_vgpr_workitem_id 2
		.amdhsa_next_free_vgpr 243
		.amdhsa_next_free_sgpr 102
		.amdhsa_accum_offset 244
		.amdhsa_reserve_vcc 1
		.amdhsa_float_round_mode_32 0
		.amdhsa_float_round_mode_16_64 0
		.amdhsa_float_denorm_mode_32 3
		.amdhsa_float_denorm_mode_16_64 3
		.amdhsa_dx10_clamp 1
		.amdhsa_ieee_mode 1
		.amdhsa_fp16_overflow 0
		.amdhsa_tg_split 0
		.amdhsa_exception_fp_ieee_invalid_op 0
		.amdhsa_exception_fp_denorm_src 0
		.amdhsa_exception_fp_ieee_div_zero 0
		.amdhsa_exception_fp_ieee_overflow 0
		.amdhsa_exception_fp_ieee_underflow 0
		.amdhsa_exception_fp_ieee_inexact 0
		.amdhsa_exception_int_div_zero 0
	.end_amdhsa_kernel

amdhsa.kernels:
  - .agpr_count:     0
    .args:
      - .offset:         0
        .size:           280
        .value_kind:     by_value
      - .offset:         280
        .size:           4
        .value_kind:     hidden_block_count_x
      - .offset:         284
        .size:           4
        .value_kind:     hidden_block_count_y
      - .offset:         288
        .size:           4
        .value_kind:     hidden_block_count_z
      - .offset:         292
        .size:           2
        .value_kind:     hidden_group_size_x
      - .offset:         294
        .size:           2
        .value_kind:     hidden_group_size_y
      - .offset:         296
        .size:           2
        .value_kind:     hidden_group_size_z
      - .offset:         298
        .size:           2
        .value_kind:     hidden_remainder_x
      - .offset:         300
        .size:           2
        .value_kind:     hidden_remainder_y
      - .offset:         302
        .size:           2
        .value_kind:     hidden_remainder_z
      - .offset:         320
        .size:           8
        .value_kind:     hidden_global_offset_x
      - .offset:         328
        .size:           8
        .value_kind:     hidden_global_offset_y
      - .offset:         336
        .size:           8
        .value_kind:     hidden_global_offset_z
      - .offset:         344
        .size:           2
        .value_kind:     hidden_grid_dims
      - .offset:         368
        .size:           8
        .value_kind:     hidden_multigrid_sync_arg
      - .offset:         400
        .size:           4
        .value_kind:     hidden_dynamic_lds_size
    .group_segment_fixed_size: 0
    .kernarg_segment_align: 8
    .kernarg_segment_size: 536
    .language:       OpenCL C
    .language_version:
      - 2
      - 0
    .max_flat_workgroup_size: 256
    .name:           _Z8fwd_mega6Params
    .private_segment_fixed_size: 0
    .sgpr_count:     108
    .sgpr_spill_count: 128
    .symbol:         _Z8fwd_mega6Params.kd
    .uniform_work_group_size: 1
    .uses_dynamic_stack: false
    .vgpr_count:     243
    .vgpr_spill_count: 0
    .wavefront_size: 64
